# x1rows: row loads issued before the ssq wait and wave reduction (wait moved to first consumer)
# speedup vs baseline: 1.0060x; 1.0004x over previous
; __device__ __forceinline__ float dot4(f32x4 a) { return (a[0] * a[0] + a[1] * a[1]) + (a[2] * a[2] + a[3] * a[3]); }
; __device__ __forceinline__ void ph_x1rows(int tbase) {
;     ...
;     for (int m = gw; m < TG; m += NGW) { const int t = tbase + m, b = t >> 12;
;         float sv = lane < 16 ? SSQ_MIX[lane * TT + t] : 0.f; sv += __shfl_xor(sv, 1); sv += __shfl_xor(sv, 2); sv += __shfl_xor(sv, 4); sv += __shfl_xor(sv, 8); sv = __shfl(sv, 0);
;         const float rs1 = rsqrtf(sv * (1.f / 1024.f) + EPS); const float* mod = MOD + b * 6144;
;         f32x4 v[4]; float s = 0.f;
; #pragma unroll
;         for (int j = 0; j < 4; ++j) { const int c0 = 4 * lane + 256 * j; const u32x2 w = *(const u32x2*)(MIX + (size_t)m * 1024 + c0);
;             const f32x4 f = {bflo(w.x), bfhi(w.x), bflo(w.y), bfhi(w.y)}; const f32x4 g = *(const f32x4*)(g_post_mix + c0), ga = *(const f32x4*)(mod + 2048 + c0);
;             v[j] = *(const f32x4*)(x + (size_t)t * 1024 + c0) + ga * (f * rs1 * g); *(f32x4*)(out + (size_t)t * 1024 + c0) = v[j]; s += dot4(v[j]); }
.LBB0_1217:
	s_or_b64 exec, exec, s[8:9]
	s_add_i32 s10, s63, s4
	s_ashr_i32 s2, s10, 12
	s_mul_i32 s8, s2, 0x1800
	s_ashr_i32 s9, s8, 31
	s_lshl_b64 s[8:9], s[8:9], 2
	s_add_u32 s5, s12, s8
	s_addc_u32 s7, s13, s9
	s_add_u32 s8, s5, 0x2000
	s_addc_u32 s9, s7, 0
	s_ashr_i32 s11, s10, 31
	s_lshl_b64 s[10:11], s[10:11], 12
	v_lshl_add_u64 v[6:7], v[22:23], 0, s[10:11]
	s_add_u32 s64, s5, 0x4000
	s_addc_u32 s65, s7, 0
	s_add_u32 s72, s5, 0x3000
	s_addc_u32 s73, s7, 0
	global_load_dwordx2 v[144:145], v[26:27], off
	global_load_dwordx2 v[146:147], v[26:27], off offset:512
	global_load_dwordx2 v[148:149], v[26:27], off offset:1024
	global_load_dwordx2 v[150:151], v[26:27], off offset:1536
	global_load_dwordx4 v[152:155], v[20:21], off
	global_load_dwordx4 v[168:171], v37, s[8:9]
	global_load_dwordx4 v[184:187], v[6:7], off
	global_load_dwordx4 v[156:159], v[20:21], off offset:1024
	global_load_dwordx4 v[172:175], v38, s[8:9]
	global_load_dwordx4 v[188:191], v[6:7], off offset:1024
	global_load_dwordx4 v[160:163], v[20:21], off offset:2048
	global_load_dwordx4 v[176:179], v39, s[8:9]
	global_load_dwordx4 v[192:195], v[6:7], off offset:2048
	global_load_dwordx4 v[164:167], v[20:21], off offset:3072
	global_load_dwordx4 v[180:183], v40, s[8:9]
	global_load_dwordx4 v[196:199], v[6:7], off offset:3072
	s_mov_b32 s2, 0xe7c00000
	s_add_i32 s4, s4, s6
	s_cmpk_lt_i32 s4, 0x4000
	s_waitcnt vmcnt(16)
	ds_bpermute_b32 v2, v30, v0
	s_waitcnt lgkmcnt(0)
	v_add_f32_e32 v0, v0, v2
	ds_bpermute_b32 v2, v31, v0
	s_waitcnt lgkmcnt(0)
	v_add_f32_e32 v0, v0, v2
	ds_bpermute_b32 v2, v32, v0
	s_waitcnt lgkmcnt(0)
	v_add_f32_e32 v0, v0, v2
	ds_bpermute_b32 v2, v33, v0
	s_waitcnt lgkmcnt(0)
	v_add_f32_e32 v0, v0, v2
	ds_bpermute_b32 v0, v244, v0
	s_waitcnt lgkmcnt(0)
	v_fmamk_f32 v0, v0, 0x3a800000, v220
	v_cmp_gt_f32_e64 s[38:39], s51, v0
	v_mul_f32_e32 v2, 0x4b800000, v0
	s_nop 0
	v_cndmask_b32_e64 v0, v0, v2, s[38:39]
	v_rsq_f32_e32 v0, v0
	s_nop 0
	v_mul_f32_e32 v2, 0x45800000, v0
	v_cndmask_b32_e64 v0, v0, v2, s[38:39]
	s_waitcnt vmcnt(12)
	v_lshlrev_b32_e32 v16, 16, v144
	v_and_b32_e32 v17, 0xffff0000, v144
	v_lshlrev_b32_e32 v28, 16, v145
	v_and_b32_e32 v29, 0xffff0000, v145
	v_pk_mul_f32 v[28:29], v[0:1], v[28:29] op_sel_hi:[0,1]
	v_pk_mul_f32 v[16:17], v[0:1], v[16:17] op_sel_hi:[0,1]
	s_waitcnt vmcnt(11)
	v_pk_mul_f32 v[2:3], v[152:153], v[16:17]
	v_pk_mul_f32 v[4:5], v[154:155], v[28:29]
	v_lshl_add_u64 v[28:29], v[24:25], 0, s[10:11]
	s_waitcnt vmcnt(9)
	v_pk_fma_f32 v[16:17], v[170:171], v[4:5], v[186:187]
	v_pk_fma_f32 v[14:15], v[168:169], v[2:3], v[184:185]
	global_store_dwordx4 v[28:29], v[14:17], off
	v_pk_mul_f32 v[2:3], v[16:17], v[16:17]
	v_pk_mul_f32 v[4:5], v[14:15], v[14:15]
	s_nop 0
	v_pk_mov_b32 v[8:9], v[4:5], v[2:3] op_sel:[1,0]
	v_mov_b32_e32 v5, v3
	v_pk_add_f32 v[50:51], v[8:9], v[4:5]
	v_lshlrev_b32_e32 v12, 16, v146
	v_and_b32_e32 v13, 0xffff0000, v146
	v_lshlrev_b32_e32 v46, 16, v147
	v_and_b32_e32 v47, 0xffff0000, v147
	v_pk_mul_f32 v[46:47], v[0:1], v[46:47] op_sel_hi:[0,1]
	v_pk_mul_f32 v[12:13], v[0:1], v[12:13] op_sel_hi:[0,1]
	s_waitcnt vmcnt(9)
	v_pk_mul_f32 v[2:3], v[156:157], v[12:13]
	v_pk_mul_f32 v[4:5], v[158:159], v[46:47]
	s_waitcnt vmcnt(7)
	v_pk_fma_f32 v[12:13], v[174:175], v[4:5], v[190:191]
	v_pk_fma_f32 v[10:11], v[172:173], v[2:3], v[188:189]
	global_store_dwordx4 v[28:29], v[10:13], off offset:1024
	v_pk_mul_f32 v[2:3], v[12:13], v[12:13]
	v_pk_mul_f32 v[4:5], v[10:11], v[10:11]
	s_nop 0
	v_pk_mov_b32 v[8:9], v[4:5], v[2:3] op_sel:[1,0]
	v_mov_b32_e32 v5, v3
	v_pk_add_f32 v[52:53], v[8:9], v[4:5]
	v_lshlrev_b32_e32 v8, 16, v148
	v_and_b32_e32 v9, 0xffff0000, v148
	v_lshlrev_b32_e32 v54, 16, v149
	v_and_b32_e32 v55, 0xffff0000, v149
	v_pk_mul_f32 v[54:55], v[0:1], v[54:55] op_sel_hi:[0,1]
	v_pk_mul_f32 v[8:9], v[0:1], v[8:9] op_sel_hi:[0,1]
	s_waitcnt vmcnt(7)
	v_pk_mul_f32 v[2:3], v[160:161], v[8:9]
	v_pk_mul_f32 v[4:5], v[162:163], v[54:55]
	s_waitcnt vmcnt(5)
	v_pk_fma_f32 v[2:3], v[176:177], v[2:3], v[192:193]
	v_pk_fma_f32 v[4:5], v[178:179], v[4:5], v[194:195]
	global_store_dwordx4 v[28:29], v[2:5], off offset:2048
	v_lshlrev_b32_e32 v54, 16, v150
	v_and_b32_e32 v55, 0xffff0000, v150
	v_lshlrev_b32_e32 v56, 16, v151
	v_and_b32_e32 v57, 0xffff0000, v151
	s_nop 0
	v_pk_mul_f32 v[56:57], v[0:1], v[56:57] op_sel_hi:[0,1]
	v_pk_mul_f32 v[54:55], v[0:1], v[54:55] op_sel_hi:[0,1]
	s_waitcnt vmcnt(5)
	v_pk_mul_f32 v[42:43], v[164:165], v[54:55]
	v_pk_mul_f32 v[44:45], v[166:167], v[56:57]
	s_waitcnt vmcnt(3)
; __device__ __forceinline__ unsigned pk2(float lo, float hi) { const f32x2 v = {lo, hi}; const bf16x2_t b = __builtin_convertvector(v, bf16x2_t); return __builtin_bit_cast(unsigned, b); }
; __device__ __forceinline__ float dot4(f32x4 a) { return (a[0] * a[0] + a[1] * a[1]) + (a[2] * a[2] + a[3] * a[3]); }
; __device__ __forceinline__ void ph_x1rows(int tbase) {
;     ...
;             v[j] = *(const f32x4*)(x + (size_t)t * 1024 + c0) + ga * (f * rs1 * g); *(f32x4*)(out + (size_t)t * 1024 + c0) = v[j]; s += dot4(v[j]); }
;         const float rs2 = rsqrtf(wave_sum(s) * (1.f / 1024.f) + EPS);
; #pragma unroll
;         for (int j = 0; j < 4; ++j) { const int c0 = 4 * lane + 256 * j; const f32x4 g = *(const f32x4*)(g_pre_mlp + c0), sc = *(const f32x4*)(mod + 4096 + c0), sh = *(const f32x4*)(mod + 3072 + c0);
;             const f32x4 hv = v[j] * rs2 * g * (sc + 1.f) + sh; u32x2 w; w.x = pk2(hv[0], hv[1]); w.y = pk2(hv[2], hv[3]); *(u32x2*)(H + (size_t)m * 1024 + c0) = w; } }
	v_pk_fma_f32 v[6:7], v[180:181], v[42:43], v[196:197]
	v_pk_fma_f32 v[8:9], v[182:183], v[44:45], v[198:199]
	global_store_dwordx4 v[28:29], v[6:9], off offset:3072
	v_mul_f32_e32 v0, v6, v6
	v_mul_f32_e32 v41, v7, v7
	v_pk_add_f32 v[28:29], v[50:51], v[50:51] op_sel:[0,1] op_sel_hi:[1,0]
	v_pk_add_f32 v[42:43], v[52:53], v[52:53] op_sel:[0,1] op_sel_hi:[1,0]
	v_mov_b32_e32 v29, v0
	v_mov_b32_e32 v43, v41
	v_mul_f32_e32 v0, v3, v3
	v_mul_f32_e32 v44, v8, v8
	v_pk_add_f32 v[28:29], v[28:29], v[42:43]
	v_pk_fma_f32 v[42:43], v[2:3], v[2:3], v[0:1] op_sel_hi:[1,1,0]
	v_mul_f32_e32 v0, v5, v5
	v_mul_f32_e32 v46, v9, v9
	v_mov_b32_e32 v43, v44
	v_pk_fma_f32 v[44:45], v[4:5], v[4:5], v[0:1] op_sel_hi:[1,1,0]
	s_nop 0
	v_mov_b32_e32 v45, v46
	v_pk_add_f32 v[42:43], v[42:43], v[44:45]
	s_nop 0
	v_pk_add_f32 v[28:29], v[28:29], v[42:43]
	global_load_dwordx4 v[42:45], v[18:19], off
	global_load_dwordx4 v[46:49], v37, s[64:65]
	global_load_dwordx4 v[50:53], v37, s[72:73]
	v_add_f32_e32 v0, v28, v29
	ds_bpermute_b32 v28, v30, v0
	s_waitcnt lgkmcnt(0)
	v_add_f32_e32 v0, v0, v28
	ds_bpermute_b32 v28, v31, v0
	s_waitcnt lgkmcnt(0)
	v_add_f32_e32 v0, v0, v28
	ds_bpermute_b32 v28, v32, v0
	s_waitcnt lgkmcnt(0)
	v_add_f32_e32 v0, v0, v28
	ds_bpermute_b32 v28, v33, v0
	s_waitcnt lgkmcnt(0)
	v_add_f32_e32 v0, v0, v28
	ds_bpermute_b32 v28, v34, v0
	s_waitcnt lgkmcnt(0)
	v_add_f32_e32 v0, v0, v28
	ds_bpermute_b32 v28, v35, v0
	s_waitcnt lgkmcnt(0)
	v_add_f32_e32 v0, v0, v28
	v_fmamk_f32 v0, v0, 0x3a800000, v220
	v_cmp_gt_f32_e64 s[38:39], s51, v0
	v_mul_f32_e32 v28, 0x4b800000, v0
	s_nop 0
	v_cndmask_b32_e64 v0, v0, v28, s[38:39]
	v_rsq_f32_e32 v0, v0
	s_nop 0
	v_mul_f32_e32 v28, 0x45800000, v0
	v_cndmask_b32_e64 v0, v0, v28, s[38:39]
	v_pk_mul_f32 v[16:17], v[16:17], v[0:1] op_sel_hi:[1,0]
	v_pk_mul_f32 v[14:15], v[14:15], v[0:1] op_sel_hi:[1,0]
	v_pk_mul_f32 v[12:13], v[12:13], v[0:1] op_sel_hi:[1,0]
	v_pk_mul_f32 v[10:11], v[10:11], v[0:1] op_sel_hi:[1,0]
	v_pk_mul_f32 v[4:5], v[4:5], v[0:1] op_sel_hi:[1,0]
	v_pk_mul_f32 v[2:3], v[2:3], v[0:1] op_sel_hi:[1,0]
	v_pk_mul_f32 v[8:9], v[8:9], v[0:1] op_sel_hi:[1,0]
	v_pk_mul_f32 v[6:7], v[6:7], v[0:1] op_sel_hi:[1,0]
	s_waitcnt vmcnt(2)
	v_pk_mul_f32 v[14:15], v[42:43], v[14:15]
	v_pk_mul_f32 v[16:17], v[44:45], v[16:17]
	s_waitcnt vmcnt(1)
	v_pk_add_f32 v[28:29], v[48:49], 1.0 op_sel_hi:[1,0]
	v_pk_add_f32 v[42:43], v[46:47], 1.0 op_sel_hi:[1,0]
	s_waitcnt vmcnt(0)
	v_pk_fma_f32 v[16:17], v[28:29], v[16:17], v[52:53]
	v_pk_fma_f32 v[14:15], v[42:43], v[14:15], v[50:51]
	s_nop 0
	v_cvt_pk_bf16_f32 v14, v14, v15
	v_cvt_pk_bf16_f32 v15, v16, v17
	v_add_co_u32_e64 v16, s[38:39], s2, v26
	s_mov_b32 s2, 0xe7c01000
	s_nop 0
	v_addc_co_u32_e64 v17, s[38:39], -1, v27, s[38:39]
	global_store_dwordx2 v[16:17], v[14:15], off
	global_load_dwordx4 v[14:17], v[18:19], off offset:1024
	s_nop 0
	global_load_dwordx4 v[42:45], v38, s[64:65]
	global_load_dwordx4 v[46:49], v38, s[72:73]
	v_add_co_u32_e64 v28, s[38:39], s2, v26
	s_waitcnt vmcnt(2)
	v_pk_mul_f32 v[10:11], v[14:15], v[10:11]
	v_pk_mul_f32 v[12:13], v[16:17], v[12:13]
	s_waitcnt vmcnt(1)
	v_pk_add_f32 v[14:15], v[44:45], 1.0 op_sel_hi:[1,0]
	v_pk_add_f32 v[16:17], v[42:43], 1.0 op_sel_hi:[1,0]
	s_waitcnt vmcnt(0)
	v_pk_fma_f32 v[12:13], v[14:15], v[12:13], v[48:49]
	v_pk_fma_f32 v[10:11], v[16:17], v[10:11], v[46:47]
	v_addc_co_u32_e64 v29, s[38:39], -1, v27, s[38:39]
	v_cvt_pk_bf16_f32 v10, v10, v11
	v_cvt_pk_bf16_f32 v11, v12, v13
	global_store_dwordx2 v[28:29], v[10:11], off offset:-3584
	global_load_dwordx4 v[10:13], v[18:19], off offset:2048
	s_nop 0
	global_load_dwordx4 v[14:17], v39, s[64:65]
	global_load_dwordx4 v[42:45], v39, s[72:73]
	v_lshl_add_u64 v[26:27], v[26:27], 0, s[42:43]
	s_waitcnt vmcnt(2)
	v_pk_mul_f32 v[2:3], v[10:11], v[2:3]
	v_pk_mul_f32 v[4:5], v[12:13], v[4:5]
	s_waitcnt vmcnt(1)
	v_pk_add_f32 v[10:11], v[16:17], 1.0 op_sel_hi:[1,0]
	v_pk_add_f32 v[12:13], v[14:15], 1.0 op_sel_hi:[1,0]
	s_waitcnt vmcnt(0)
	v_pk_fma_f32 v[4:5], v[10:11], v[4:5], v[44:45]
	v_pk_fma_f32 v[2:3], v[12:13], v[2:3], v[42:43]
	s_nop 0
	v_cvt_pk_bf16_f32 v2, v2, v3
	v_cvt_pk_bf16_f32 v3, v4, v5
	global_store_dwordx2 v[28:29], v[2:3], off offset:-3072
	global_load_dwordx4 v[2:5], v[18:19], off offset:3072
	s_nop 0
	global_load_dwordx4 v[10:13], v40, s[64:65]
	global_load_dwordx4 v[14:17], v40, s[72:73]
	s_waitcnt vmcnt(2)
	v_pk_mul_f32 v[2:3], v[2:3], v[6:7]
	v_pk_mul_f32 v[4:5], v[4:5], v[8:9]
	s_waitcnt vmcnt(1)
	v_pk_add_f32 v[6:7], v[12:13], 1.0 op_sel_hi:[1,0]
	v_pk_add_f32 v[8:9], v[10:11], 1.0 op_sel_hi:[1,0]
	s_waitcnt vmcnt(0)
	v_pk_fma_f32 v[4:5], v[6:7], v[4:5], v[16:17]
	v_pk_fma_f32 v[2:3], v[8:9], v[2:3], v[14:15]
	s_nop 0
	v_cvt_pk_bf16_f32 v2, v2, v3
	v_cvt_pk_bf16_f32 v3, v4, v5
	global_store_dwordx2 v[28:29], v[2:3], off offset:-2560
	s_cbranch_scc0 .LBB0_1220
